# v11 + convgate A-row loads prefetched one trip ahead (issued in the tail of the previous trip, first trip in the pre-header)
# baseline (speedup 1.0000x reference)
.LBB0_1324:
	v_lshl_add_u32 v82, v154, 1, 0
	v_add_u32_e32 v170, v82, v153
	s_movk_i32 s4, 0xffc0
	v_ashrrev_i32_e32 v153, 31, v152
	v_cmp_lt_i32_e64 s[70:71], s4, v157
	v_lshl_add_u64 v[80:81], v[152:153], 1, s[28:29]
	s_mov_b64 s[4:5], 0x51b2000
	v_lshl_add_u64 v[116:117], v[80:81], 0, s[4:5]
	v_lshlrev_b32_e32 v80, 11, v157
	s_mul_i32 s4, s40, 0x8400
	v_add_u32_e32 v171, v82, v80
	v_add_u32_e32 v80, s4, v80
	v_and_b32_e32 v81, 31, v156
	v_lshl_or_b32 v80, v81, 4, v80
	v_readlane_b32 s4, v240, 29
	v_cmp_gt_u32_e64 s[44:45], 64, v140
	v_cmp_lt_i32_e64 s[46:47], 0, v157
	v_add_u32_e32 v172, s4, v80
	s_lshl_b32 s4, s40, 6
	v_lshl_add_u32 v81, v157, 2, s4
	v_readlane_b32 s4, v240, 30
	v_cmp_gt_i32_e64 s[48:49], s61, v157
	v_cmp_gt_u32_e64 s[50:51], 64, v144
	v_cmp_lt_i32_e64 s[52:53], -16, v157
	v_cmp_gt_i32_e64 s[54:55], 49, v157
	v_cmp_gt_u32_e64 s[56:57], 64, v146
	v_cmp_lt_i32_e64 s[58:59], s60, v157
	v_cmp_gt_i32_e64 s[60:61], 33, v157
	v_cmp_gt_u32_e64 s[62:63], 64, v148
	v_cmp_lt_i32_e64 s[64:65], s64, v157
	v_cmp_gt_i32_e64 s[66:67], 17, v157
	v_cmp_gt_u32_e64 s[68:69], 64, v150
	v_cmp_gt_i32_e64 s[72:73], 1, v157
	s_add_i32 s26, s40, 4
	v_or_b32_e32 v182, 3, v81
	v_add_u32_e32 v183, s4, v80
	s_add_i32 s41, s40, 2
	v_add_u32_e32 v100, -3, v182
	v_mad_i64_i32 v[100:101], s[4:5], s35, v100, 0
	v_lshl_add_u64 v[124:125], v[100:101], 1, v[116:117]
	v_add_u32_e32 v100, -2, v182
	v_mad_i64_i32 v[100:101], s[4:5], s35, v100, 0
	v_lshl_add_u64 v[122:123], v[100:101], 1, v[116:117]
	v_add_u32_e32 v100, -1, v182
	v_mad_i64_i32 v[100:101], s[4:5], s35, v100, 0
	v_lshl_add_u64 v[120:121], v[100:101], 1, v[116:117]
	v_mad_i64_i32 v[100:101], s[4:5], s35, v182, 0
	global_load_dwordx4 v[112:115], v[124:125], off nt
	global_load_dwordx4 v[108:111], v[122:123], off nt
	v_lshl_add_u64 v[118:119], v[100:101], 1, v[116:117]
	global_load_dwordx4 v[104:107], v[120:121], off nt
	global_load_dwordx4 v[100:103], v[118:119], off nt
	s_waitcnt lgkmcnt(0)
	s_barrier
	s_branch .LBB0_1327

.LBB0_1326:
	v_add_u32_e32 v172, 0x8400, v172
	s_add_i32 s26, s26, 1
	v_add_u32_e32 v182, 64, v182
	v_add_u32_e32 v183, 0x8400, v183
	s_add_i32 s41, s41, 1
	s_andn2_b64 vcc, exec, s[28:29]
	s_cbranch_vccz .Lcg_nopref
	v_add_u32_e32 v100, -3, v182
	v_mad_i64_i32 v[100:101], s[4:5], s35, v100, 0
	v_lshl_add_u64 v[124:125], v[100:101], 1, v[116:117]
	v_add_u32_e32 v100, -2, v182
	v_mad_i64_i32 v[100:101], s[4:5], s35, v100, 0
	v_lshl_add_u64 v[122:123], v[100:101], 1, v[116:117]
	v_add_u32_e32 v100, -1, v182
	v_mad_i64_i32 v[100:101], s[4:5], s35, v100, 0
	v_lshl_add_u64 v[120:121], v[100:101], 1, v[116:117]
	v_mad_i64_i32 v[100:101], s[4:5], s35, v182, 0
	global_load_dwordx4 v[112:115], v[124:125], off nt
	global_load_dwordx4 v[108:111], v[122:123], off nt
	v_lshl_add_u64 v[118:119], v[100:101], 1, v[116:117]
	global_load_dwordx4 v[104:107], v[120:121], off nt
	global_load_dwordx4 v[100:103], v[118:119], off nt
.Lcg_nopref:
	s_mov_b32 s40, s31
	s_waitcnt lgkmcnt(0)
	s_barrier
	s_cbranch_vccz .LBB0_1346
.LBB0_1327:
	s_add_i32 s90, s40, 2
	s_cmpk_lt_i32 s40, 0x17e
	s_cselect_b64 s[4:5], -1, 0
	s_add_i32 s31, s40, 1
	s_cmp_ge_i32 s31, s77
	s_cselect_b64 s[28:29], -1, 0
	s_cmp_lt_i32 s31, s77
	s_cselect_b64 s[8:9], -1, 0
	s_and_b64 s[4:5], s[4:5], s[8:9]
	v_cndmask_b32_e64 v239, 0, 1, s[4:5]
	v_cmp_ne_u32_e64 s[74:75], 1, v239
	s_andn2_b64 vcc, exec, s[4:5]
	s_cbranch_vccnz .LBB0_1339
	s_cmpk_lt_i32 s40, 0x7e
	s_cselect_b64 vcc, -1, 0
	s_and_b32 s4, s90, 3
	s_cmp_lg_u32 s4, 0
	s_cselect_b64 s[8:9], -1, 0
	s_cmp_lg_u32 s4, 3
	s_cselect_b64 s[92:93], -1, 0
	s_or_b64 s[78:79], s[46:47], s[8:9]
	s_or_b64 s[94:95], s[48:49], s[92:93]
	s_and_b64 s[78:79], s[78:79], s[94:95]
	v_cndmask_b32_e64 v80, 0, 1, s[44:45]
	v_cndmask_b32_e64 v81, 0, 1, s[78:79]
	v_cndmask_b32_e32 v80, v80, v81, vcc
	s_ashr_i32 s91, s90, 31
	v_and_b32_e32 v80, 1, v80
	s_lshl_b64 s[4:5], s[90:91], 6
	v_cmp_eq_u32_e64 s[78:79], 1, v80
	v_mov_b32_e32 v84, 0
	v_mov_b32_e32 v80, 0
	v_mov_b32_e32 v81, 0
	v_mov_b32_e32 v82, 0
	v_mov_b32_e32 v83, 0
	s_and_saveexec_b64 s[94:95], s[78:79]
	s_cbranch_execz .LBB0_1330
	v_lshl_add_u64 v[80:81], s[4:5], 0, v[140:141]
	v_mad_u64_u32 v[82:83], s[78:79], v80, s35, 0
	v_mad_i32_i24 v83, v81, s35, v83
	v_lshl_add_u64 v[80:81], v[82:83], 1, v[142:143]
	global_load_dwordx4 v[80:83], v[80:81], off nt
